# RESID epilogue stores write-through (sc1) so the grid barrier L2 writeback has less dirty data
# baseline (speedup 1.0000x reference)
; __device__ __forceinline__ unsigned cvt_pk_bf16(float lo, float hi) { unsigned r; asm volatile("v_cvt_pk_bf16_f32 %0, %1, %2" : "=v"(r) : "v"(lo), "v"(hi)); return r; }
; __device__ __forceinline__ float bflo(unsigned w) { return __uint_as_float(w << 16); }
; __device__ __forceinline__ float bfhi(unsigned w) { return __uint_as_float(w & 0xffff0000u); }
; __device__ __forceinline__ void epi_resid(const f32x4 (&acc)[2][2][4][2], const Unit& u, char* Cb, int ldc, const float* bias, int wr, int wc, int fr, int fq) {
;     const int col0 = u.pn * BM + wc * 32 + 8 * fq;
;     bf16_t* base = (bf16_t*)Cb + (long)(u.pm * BM + wr * 64 + fr) * ldc + col0;
; #pragma unroll
;     for (int bj = 0; bj < 2; ++bj) {
;         const f32x4 b0 = bias ? *(const f32x4*)(bias + col0 + bj * HALF) : (f32x4){0.f, 0.f, 0.f, 0.f};
;         const f32x4 b1 = bias ? *(const f32x4*)(bias + col0 + bj * HALF + 4) : (f32x4){0.f, 0.f, 0.f, 0.f};
; #pragma unroll
;         for (int ai = 0; ai < 2; ++ai)
; #pragma unroll
;             for (int m = 0; m < 4; ++m) { u32x4* q = (u32x4*)(base + (long)(ai * HALF + m * 16) * ldc + bj * HALF);
;                 const u32x4 x = *q; const f32x4 a0 = acc[ai][bj][m][0], a1 = acc[ai][bj][m][1];
;                 u32x4 w;
;                 w.x = cvt_pk_bf16(bflo(x.x) + a0[0] + b0[0], bfhi(x.x) + a0[1] + b0[1]); w.y = cvt_pk_bf16(bflo(x.y) + a0[2] + b0[2], bfhi(x.y) + a0[3] + b0[3]);
;                 w.z = cvt_pk_bf16(bflo(x.z) + a1[0] + b1[0], bfhi(x.z) + a1[1] + b1[1]); w.w = cvt_pk_bf16(bflo(x.w) + a1[2] + b1[2], bfhi(x.w) + a1[3] + b1[3]);
;                 *q = w; } }
; }
.Lres_nobias:
	global_load_dwordx4 v[134:137], v[220:221], off
	v_lshl_add_u64 v[222:223], v[220:221], 0, s[14:15]
	global_load_dwordx4 v[138:141], v[222:223], off
	v_lshl_add_u64 v[222:223], v[222:223], 0, s[14:15]
	global_load_dwordx4 v[142:145], v[222:223], off
	v_lshl_add_u64 v[222:223], v[222:223], 0, s[14:15]
	global_load_dwordx4 v[146:149], v[222:223], off
	v_lshl_add_u64 v[222:223], v[222:223], 0, s[2:3]
	global_load_dwordx4 v[150:153], v[222:223], off
	v_lshl_add_u64 v[222:223], v[222:223], 0, s[14:15]
	global_load_dwordx4 v[154:157], v[222:223], off
	v_lshl_add_u64 v[222:223], v[222:223], 0, s[14:15]
	global_load_dwordx4 v[182:185], v[222:223], off
	v_lshl_add_u64 v[222:223], v[222:223], 0, s[14:15]
	global_load_dwordx4 v[186:189], v[222:223], off
	global_load_dwordx4 v[190:193], v[220:221], off offset:256
	v_lshl_add_u64 v[222:223], v[220:221], 0, s[14:15]
	global_load_dwordx4 v[194:197], v[222:223], off offset:256
	v_lshl_add_u64 v[222:223], v[222:223], 0, s[14:15]
	global_load_dwordx4 v[198:201], v[222:223], off offset:256
	v_lshl_add_u64 v[222:223], v[222:223], 0, s[14:15]
	global_load_dwordx4 v[202:205], v[222:223], off offset:256
	v_mov_b64_e32 v[224:225], v[220:221]
	s_waitcnt vmcnt(11)
	v_lshlrev_b32_e32 v10, 16, v134
	v_and_b32_e32 v134, 0xffff0000, v134
	v_add_f32_e32 v10, v130, v10
	v_add_f32_e32 v134, v131, v134
	v_add_f32_e32 v10, v206, v10
	v_add_f32_e32 v134, v207, v134
	v_cvt_pk_bf16_f32 v134, v10, v134
	v_lshlrev_b32_e32 v10, 16, v135
	v_and_b32_e32 v135, 0xffff0000, v135
	v_add_f32_e32 v10, v132, v10
	v_add_f32_e32 v135, v133, v135
	v_add_f32_e32 v10, v208, v10
	v_add_f32_e32 v135, v209, v135
	v_cvt_pk_bf16_f32 v135, v10, v135
	v_lshlrev_b32_e32 v10, 16, v136
	v_and_b32_e32 v136, 0xffff0000, v136
	v_add_f32_e32 v10, v126, v10
	v_add_f32_e32 v136, v127, v136
	v_add_f32_e32 v10, v242, v10
	v_add_f32_e32 v136, v243, v136
	v_cvt_pk_bf16_f32 v136, v10, v136
	v_lshlrev_b32_e32 v10, 16, v137
	v_and_b32_e32 v137, 0xffff0000, v137
	v_add_f32_e32 v10, v128, v10
	v_add_f32_e32 v137, v129, v137
	v_add_f32_e32 v10, v244, v10
	v_add_f32_e32 v137, v245, v137
	v_cvt_pk_bf16_f32 v137, v10, v137
	global_store_dwordx4 v[224:225], v[134:137], off sc1
	v_lshl_add_u64 v[224:225], v[224:225], 0, s[14:15]
	s_nop 0
	v_lshl_add_u64 v[222:223], v[222:223], 0, s[2:3]
	global_load_dwordx4 v[134:137], v[222:223], off offset:256
	s_waitcnt vmcnt(12)
	v_lshlrev_b32_e32 v10, 16, v138
	v_and_b32_e32 v138, 0xffff0000, v138
	v_add_f32_e32 v10, v114, v10
	v_add_f32_e32 v138, v115, v138
	v_add_f32_e32 v10, v206, v10
	v_add_f32_e32 v138, v207, v138
	v_cvt_pk_bf16_f32 v138, v10, v138
	v_lshlrev_b32_e32 v10, 16, v139
	v_and_b32_e32 v139, 0xffff0000, v139
	v_add_f32_e32 v10, v116, v10
	v_add_f32_e32 v139, v117, v139
	v_add_f32_e32 v10, v208, v10
	v_add_f32_e32 v139, v209, v139
	v_cvt_pk_bf16_f32 v139, v10, v139
	v_lshlrev_b32_e32 v10, 16, v140
	v_and_b32_e32 v140, 0xffff0000, v140
	v_add_f32_e32 v10, v110, v10
	v_add_f32_e32 v140, v111, v140
	v_add_f32_e32 v10, v242, v10
	v_add_f32_e32 v140, v243, v140
	v_cvt_pk_bf16_f32 v140, v10, v140
	v_lshlrev_b32_e32 v10, 16, v141
	v_and_b32_e32 v141, 0xffff0000, v141
	v_add_f32_e32 v10, v112, v10
	v_add_f32_e32 v141, v113, v141
	v_add_f32_e32 v10, v244, v10
	v_add_f32_e32 v141, v245, v141
	v_cvt_pk_bf16_f32 v141, v10, v141
	global_store_dwordx4 v[224:225], v[138:141], off sc1
	v_lshl_add_u64 v[224:225], v[224:225], 0, s[14:15]
	s_nop 0
	v_lshl_add_u64 v[222:223], v[222:223], 0, s[14:15]
	global_load_dwordx4 v[138:141], v[222:223], off offset:256
	s_waitcnt vmcnt(13)
	v_lshlrev_b32_e32 v10, 16, v142
	v_and_b32_e32 v142, 0xffff0000, v142
	v_add_f32_e32 v10, v98, v10
	v_add_f32_e32 v142, v99, v142
	v_add_f32_e32 v10, v206, v10
	v_add_f32_e32 v142, v207, v142
	v_cvt_pk_bf16_f32 v142, v10, v142
	v_lshlrev_b32_e32 v10, 16, v143
	v_and_b32_e32 v143, 0xffff0000, v143
	v_add_f32_e32 v10, v100, v10
	v_add_f32_e32 v143, v101, v143
	v_add_f32_e32 v10, v208, v10
	v_add_f32_e32 v143, v209, v143
	v_cvt_pk_bf16_f32 v143, v10, v143
	v_lshlrev_b32_e32 v10, 16, v144
	v_and_b32_e32 v144, 0xffff0000, v144
	v_add_f32_e32 v10, v94, v10
	v_add_f32_e32 v144, v95, v144
	v_add_f32_e32 v10, v242, v10
	v_add_f32_e32 v144, v243, v144
	v_cvt_pk_bf16_f32 v144, v10, v144
	v_lshlrev_b32_e32 v10, 16, v145
	v_and_b32_e32 v145, 0xffff0000, v145
	v_add_f32_e32 v10, v96, v10
	v_add_f32_e32 v145, v97, v145
	v_add_f32_e32 v10, v244, v10
	v_add_f32_e32 v145, v245, v145
	v_cvt_pk_bf16_f32 v145, v10, v145
	global_store_dwordx4 v[224:225], v[142:145], off sc1
	v_lshl_add_u64 v[224:225], v[224:225], 0, s[14:15]
	s_nop 0
	v_lshl_add_u64 v[222:223], v[222:223], 0, s[14:15]
	global_load_dwordx4 v[142:145], v[222:223], off offset:256
	s_waitcnt vmcnt(14)
	v_lshlrev_b32_e32 v10, 16, v146
	v_and_b32_e32 v146, 0xffff0000, v146
	v_add_f32_e32 v10, v82, v10
	v_add_f32_e32 v146, v83, v146
	v_add_f32_e32 v10, v206, v10
	v_add_f32_e32 v146, v207, v146
	v_cvt_pk_bf16_f32 v146, v10, v146
	v_lshlrev_b32_e32 v10, 16, v147
	v_and_b32_e32 v147, 0xffff0000, v147
	v_add_f32_e32 v10, v84, v10
	v_add_f32_e32 v147, v85, v147
	v_add_f32_e32 v10, v208, v10
	v_add_f32_e32 v147, v209, v147
	v_cvt_pk_bf16_f32 v147, v10, v147
	v_lshlrev_b32_e32 v10, 16, v148
	v_and_b32_e32 v148, 0xffff0000, v148
	v_add_f32_e32 v10, v78, v10
	v_add_f32_e32 v148, v79, v148
	v_add_f32_e32 v10, v242, v10
	v_add_f32_e32 v148, v243, v148
	v_cvt_pk_bf16_f32 v148, v10, v148
	v_lshlrev_b32_e32 v10, 16, v149
	v_and_b32_e32 v149, 0xffff0000, v149
	v_add_f32_e32 v10, v80, v10
	v_add_f32_e32 v149, v81, v149
	v_add_f32_e32 v10, v244, v10
	v_add_f32_e32 v149, v245, v149
	v_cvt_pk_bf16_f32 v149, v10, v149
	global_store_dwordx4 v[224:225], v[146:149], off sc1
	v_lshl_add_u64 v[224:225], v[224:225], 0, s[2:3]
	s_nop 0
	v_lshl_add_u64 v[222:223], v[222:223], 0, s[14:15]
	global_load_dwordx4 v[146:149], v[222:223], off offset:256
	s_waitcnt vmcnt(15)
; __device__ __forceinline__ unsigned cvt_pk_bf16(float lo, float hi) { unsigned r; asm volatile("v_cvt_pk_bf16_f32 %0, %1, %2" : "=v"(r) : "v"(lo), "v"(hi)); return r; }
; __device__ __forceinline__ float bflo(unsigned w) { return __uint_as_float(w << 16); }
; __device__ __forceinline__ float bfhi(unsigned w) { return __uint_as_float(w & 0xffff0000u); }
; __device__ __forceinline__ void epi_resid(const f32x4 (&acc)[2][2][4][2], const Unit& u, char* Cb, int ldc, const float* bias, int wr, int wc, int fr, int fq) {
;     const int col0 = u.pn * BM + wc * 32 + 8 * fq;
;     bf16_t* base = (bf16_t*)Cb + (long)(u.pm * BM + wr * 64 + fr) * ldc + col0;
; #pragma unroll
;     for (int bj = 0; bj < 2; ++bj) {
;         const f32x4 b0 = bias ? *(const f32x4*)(bias + col0 + bj * HALF) : (f32x4){0.f, 0.f, 0.f, 0.f};
;         const f32x4 b1 = bias ? *(const f32x4*)(bias + col0 + bj * HALF + 4) : (f32x4){0.f, 0.f, 0.f, 0.f};
; #pragma unroll
;         for (int ai = 0; ai < 2; ++ai)
; #pragma unroll
;             for (int m = 0; m < 4; ++m) { u32x4* q = (u32x4*)(base + (long)(ai * HALF + m * 16) * ldc + bj * HALF);
;                 const u32x4 x = *q; const f32x4 a0 = acc[ai][bj][m][0], a1 = acc[ai][bj][m][1];
;                 u32x4 w;
;                 w.x = cvt_pk_bf16(bflo(x.x) + a0[0] + b0[0], bfhi(x.x) + a0[1] + b0[1]); w.y = cvt_pk_bf16(bflo(x.y) + a0[2] + b0[2], bfhi(x.y) + a0[3] + b0[3]);
;                 w.z = cvt_pk_bf16(bflo(x.z) + a1[0] + b1[0], bfhi(x.z) + a1[1] + b1[1]); w.w = cvt_pk_bf16(bflo(x.w) + a1[2] + b1[2], bfhi(x.w) + a1[3] + b1[3]);
;                 *q = w; } }
; }
	v_lshlrev_b32_e32 v10, 16, v150
	v_and_b32_e32 v150, 0xffff0000, v150
	v_add_f32_e32 v10, v66, v10
	v_add_f32_e32 v150, v67, v150
	v_add_f32_e32 v10, v206, v10
	v_add_f32_e32 v150, v207, v150
	v_cvt_pk_bf16_f32 v150, v10, v150
	v_lshlrev_b32_e32 v10, 16, v151
	v_and_b32_e32 v151, 0xffff0000, v151
	v_add_f32_e32 v10, v68, v10
	v_add_f32_e32 v151, v69, v151
	v_add_f32_e32 v10, v208, v10
	v_add_f32_e32 v151, v209, v151
	v_cvt_pk_bf16_f32 v151, v10, v151
	v_lshlrev_b32_e32 v10, 16, v152
	v_and_b32_e32 v152, 0xffff0000, v152
	v_add_f32_e32 v10, v62, v10
	v_add_f32_e32 v152, v63, v152
	v_add_f32_e32 v10, v242, v10
	v_add_f32_e32 v152, v243, v152
	v_cvt_pk_bf16_f32 v152, v10, v152
	v_lshlrev_b32_e32 v10, 16, v153
	v_and_b32_e32 v153, 0xffff0000, v153
	v_add_f32_e32 v10, v64, v10
	v_add_f32_e32 v153, v65, v153
	v_add_f32_e32 v10, v244, v10
	v_add_f32_e32 v153, v245, v153
	v_cvt_pk_bf16_f32 v153, v10, v153
	global_store_dwordx4 v[224:225], v[150:153], off sc1
	v_lshl_add_u64 v[224:225], v[224:225], 0, s[14:15]
	s_waitcnt vmcnt(15)
	v_lshlrev_b32_e32 v10, 16, v154
	v_and_b32_e32 v154, 0xffff0000, v154
	v_add_f32_e32 v10, v50, v10
	v_add_f32_e32 v154, v51, v154
	v_add_f32_e32 v10, v206, v10
	v_add_f32_e32 v154, v207, v154
	v_cvt_pk_bf16_f32 v154, v10, v154
	v_lshlrev_b32_e32 v10, 16, v155
	v_and_b32_e32 v155, 0xffff0000, v155
	v_add_f32_e32 v10, v52, v10
	v_add_f32_e32 v155, v53, v155
	v_add_f32_e32 v10, v208, v10
	v_add_f32_e32 v155, v209, v155
	v_cvt_pk_bf16_f32 v155, v10, v155
	v_lshlrev_b32_e32 v10, 16, v156
	v_and_b32_e32 v156, 0xffff0000, v156
	v_add_f32_e32 v10, v46, v10
	v_add_f32_e32 v156, v47, v156
	v_add_f32_e32 v10, v242, v10
	v_add_f32_e32 v156, v243, v156
	v_cvt_pk_bf16_f32 v156, v10, v156
	v_lshlrev_b32_e32 v10, 16, v157
	v_and_b32_e32 v157, 0xffff0000, v157
	v_add_f32_e32 v10, v48, v10
	v_add_f32_e32 v157, v49, v157
	v_add_f32_e32 v10, v244, v10
	v_add_f32_e32 v157, v245, v157
	v_cvt_pk_bf16_f32 v157, v10, v157
	global_store_dwordx4 v[224:225], v[154:157], off sc1
	v_lshl_add_u64 v[224:225], v[224:225], 0, s[14:15]
	s_waitcnt vmcnt(15)
	v_lshlrev_b32_e32 v10, 16, v182
	v_and_b32_e32 v182, 0xffff0000, v182
	v_add_f32_e32 v10, v34, v10
	v_add_f32_e32 v182, v35, v182
	v_add_f32_e32 v10, v206, v10
	v_add_f32_e32 v182, v207, v182
	v_cvt_pk_bf16_f32 v182, v10, v182
	v_lshlrev_b32_e32 v10, 16, v183
	v_and_b32_e32 v183, 0xffff0000, v183
	v_add_f32_e32 v10, v36, v10
	v_add_f32_e32 v183, v37, v183
	v_add_f32_e32 v10, v208, v10
	v_add_f32_e32 v183, v209, v183
	v_cvt_pk_bf16_f32 v183, v10, v183
	v_lshlrev_b32_e32 v10, 16, v184
	v_and_b32_e32 v184, 0xffff0000, v184
	v_add_f32_e32 v10, v30, v10
	v_add_f32_e32 v184, v31, v184
	v_add_f32_e32 v10, v242, v10
	v_add_f32_e32 v184, v243, v184
	v_cvt_pk_bf16_f32 v184, v10, v184
	v_lshlrev_b32_e32 v10, 16, v185
	v_and_b32_e32 v185, 0xffff0000, v185
	v_add_f32_e32 v10, v32, v10
	v_add_f32_e32 v185, v33, v185
	v_add_f32_e32 v10, v244, v10
	v_add_f32_e32 v185, v245, v185
	v_cvt_pk_bf16_f32 v185, v10, v185
	global_store_dwordx4 v[224:225], v[182:185], off sc1
	v_lshl_add_u64 v[224:225], v[224:225], 0, s[14:15]
	s_waitcnt vmcnt(15)
	v_lshlrev_b32_e32 v10, 16, v186
	v_and_b32_e32 v186, 0xffff0000, v186
	v_add_f32_e32 v10, v18, v10
	v_add_f32_e32 v186, v19, v186
	v_add_f32_e32 v10, v206, v10
	v_add_f32_e32 v186, v207, v186
	v_cvt_pk_bf16_f32 v186, v10, v186
	v_lshlrev_b32_e32 v10, 16, v187
	v_and_b32_e32 v187, 0xffff0000, v187
	v_add_f32_e32 v10, v20, v10
	v_add_f32_e32 v187, v21, v187
	v_add_f32_e32 v10, v208, v10
	v_add_f32_e32 v187, v209, v187
	v_cvt_pk_bf16_f32 v187, v10, v187
	v_lshlrev_b32_e32 v10, 16, v188
	v_and_b32_e32 v188, 0xffff0000, v188
	v_add_f32_e32 v10, v14, v10
	v_add_f32_e32 v188, v15, v188
	v_add_f32_e32 v10, v242, v10
	v_add_f32_e32 v188, v243, v188
	v_cvt_pk_bf16_f32 v188, v10, v188
	v_lshlrev_b32_e32 v10, 16, v189
	v_and_b32_e32 v189, 0xffff0000, v189
	v_add_f32_e32 v10, v16, v10
	v_add_f32_e32 v189, v17, v189
	v_add_f32_e32 v10, v244, v10
	v_add_f32_e32 v189, v245, v189
	v_cvt_pk_bf16_f32 v189, v10, v189
	global_store_dwordx4 v[224:225], v[186:189], off sc1
	v_mov_b64_e32 v[224:225], v[220:221]
	s_waitcnt vmcnt(15)
	v_lshlrev_b32_e32 v10, 16, v190
	v_and_b32_e32 v190, 0xffff0000, v190
	v_add_f32_e32 v10, v122, v10
	v_add_f32_e32 v190, v123, v190
	v_add_f32_e32 v10, v246, v10
	v_add_f32_e32 v190, v247, v190
	v_cvt_pk_bf16_f32 v190, v10, v190
	v_lshlrev_b32_e32 v10, 16, v191
	v_and_b32_e32 v191, 0xffff0000, v191
	v_add_f32_e32 v10, v124, v10
	v_add_f32_e32 v191, v125, v191
	v_add_f32_e32 v10, v248, v10
	v_add_f32_e32 v191, v249, v191
	v_cvt_pk_bf16_f32 v191, v10, v191
	v_lshlrev_b32_e32 v10, 16, v192
	v_and_b32_e32 v192, 0xffff0000, v192
	v_add_f32_e32 v10, v118, v10
	v_add_f32_e32 v192, v119, v192
	v_add_f32_e32 v10, v250, v10
	v_add_f32_e32 v192, v251, v192
	v_cvt_pk_bf16_f32 v192, v10, v192
	v_lshlrev_b32_e32 v10, 16, v193
	v_and_b32_e32 v193, 0xffff0000, v193
	v_add_f32_e32 v10, v120, v10
	v_add_f32_e32 v193, v121, v193
	v_add_f32_e32 v10, v252, v10
	v_add_f32_e32 v193, v253, v193
	v_cvt_pk_bf16_f32 v193, v10, v193
	global_store_dwordx4 v[224:225], v[190:193], off offset:256 sc1
	v_lshl_add_u64 v[224:225], v[224:225], 0, s[14:15]
	s_waitcnt vmcnt(15)
; __device__ __forceinline__ unsigned cvt_pk_bf16(float lo, float hi) { unsigned r; asm volatile("v_cvt_pk_bf16_f32 %0, %1, %2" : "=v"(r) : "v"(lo), "v"(hi)); return r; }
; __device__ __forceinline__ float bflo(unsigned w) { return __uint_as_float(w << 16); }
; __device__ __forceinline__ float bfhi(unsigned w) { return __uint_as_float(w & 0xffff0000u); }
; __device__ __forceinline__ void epi_resid(const f32x4 (&acc)[2][2][4][2], const Unit& u, char* Cb, int ldc, const float* bias, int wr, int wc, int fr, int fq) {
;     ...
;             for (int m = 0; m < 4; ++m) { u32x4* q = (u32x4*)(base + (long)(ai * HALF + m * 16) * ldc + bj * HALF);
;                 const u32x4 x = *q; const f32x4 a0 = acc[ai][bj][m][0], a1 = acc[ai][bj][m][1];
;                 u32x4 w;
;                 w.x = cvt_pk_bf16(bflo(x.x) + a0[0] + b0[0], bfhi(x.x) + a0[1] + b0[1]); w.y = cvt_pk_bf16(bflo(x.y) + a0[2] + b0[2], bfhi(x.y) + a0[3] + b0[3]);
;                 w.z = cvt_pk_bf16(bflo(x.z) + a1[0] + b1[0], bfhi(x.z) + a1[1] + b1[1]); w.w = cvt_pk_bf16(bflo(x.w) + a1[2] + b1[2], bfhi(x.w) + a1[3] + b1[3]);
;                 *q = w; } }
	v_lshlrev_b32_e32 v10, 16, v194
	v_and_b32_e32 v194, 0xffff0000, v194
	v_add_f32_e32 v10, v106, v10
	v_add_f32_e32 v194, v107, v194
	v_add_f32_e32 v10, v246, v10
	v_add_f32_e32 v194, v247, v194
	v_cvt_pk_bf16_f32 v194, v10, v194
	v_lshlrev_b32_e32 v10, 16, v195
	v_and_b32_e32 v195, 0xffff0000, v195
	v_add_f32_e32 v10, v108, v10
	v_add_f32_e32 v195, v109, v195
	v_add_f32_e32 v10, v248, v10
	v_add_f32_e32 v195, v249, v195
	v_cvt_pk_bf16_f32 v195, v10, v195
	v_lshlrev_b32_e32 v10, 16, v196
	v_and_b32_e32 v196, 0xffff0000, v196
	v_add_f32_e32 v10, v102, v10
	v_add_f32_e32 v196, v103, v196
	v_add_f32_e32 v10, v250, v10
	v_add_f32_e32 v196, v251, v196
	v_cvt_pk_bf16_f32 v196, v10, v196
	v_lshlrev_b32_e32 v10, 16, v197
	v_and_b32_e32 v197, 0xffff0000, v197
	v_add_f32_e32 v10, v104, v10
	v_add_f32_e32 v197, v105, v197
	v_add_f32_e32 v10, v252, v10
	v_add_f32_e32 v197, v253, v197
	v_cvt_pk_bf16_f32 v197, v10, v197
	global_store_dwordx4 v[224:225], v[194:197], off offset:256 sc1
	v_lshl_add_u64 v[224:225], v[224:225], 0, s[14:15]
	s_waitcnt vmcnt(15)
	v_lshlrev_b32_e32 v10, 16, v198
	v_and_b32_e32 v198, 0xffff0000, v198
	v_add_f32_e32 v10, v90, v10
	v_add_f32_e32 v198, v91, v198
	v_add_f32_e32 v10, v246, v10
	v_add_f32_e32 v198, v247, v198
	v_cvt_pk_bf16_f32 v198, v10, v198
	v_lshlrev_b32_e32 v10, 16, v199
	v_and_b32_e32 v199, 0xffff0000, v199
	v_add_f32_e32 v10, v92, v10
	v_add_f32_e32 v199, v93, v199
	v_add_f32_e32 v10, v248, v10
	v_add_f32_e32 v199, v249, v199
	v_cvt_pk_bf16_f32 v199, v10, v199
	v_lshlrev_b32_e32 v10, 16, v200
	v_and_b32_e32 v200, 0xffff0000, v200
	v_add_f32_e32 v10, v86, v10
	v_add_f32_e32 v200, v87, v200
	v_add_f32_e32 v10, v250, v10
	v_add_f32_e32 v200, v251, v200
	v_cvt_pk_bf16_f32 v200, v10, v200
	v_lshlrev_b32_e32 v10, 16, v201
	v_and_b32_e32 v201, 0xffff0000, v201
	v_add_f32_e32 v10, v88, v10
	v_add_f32_e32 v201, v89, v201
	v_add_f32_e32 v10, v252, v10
	v_add_f32_e32 v201, v253, v201
	v_cvt_pk_bf16_f32 v201, v10, v201
	global_store_dwordx4 v[224:225], v[198:201], off offset:256 sc1
	v_lshl_add_u64 v[224:225], v[224:225], 0, s[14:15]
	s_waitcnt vmcnt(15)
	v_lshlrev_b32_e32 v10, 16, v202
	v_and_b32_e32 v202, 0xffff0000, v202
	v_add_f32_e32 v10, v74, v10
	v_add_f32_e32 v202, v75, v202
	v_add_f32_e32 v10, v246, v10
	v_add_f32_e32 v202, v247, v202
	v_cvt_pk_bf16_f32 v202, v10, v202
	v_lshlrev_b32_e32 v10, 16, v203
	v_and_b32_e32 v203, 0xffff0000, v203
	v_add_f32_e32 v10, v76, v10
	v_add_f32_e32 v203, v77, v203
	v_add_f32_e32 v10, v248, v10
	v_add_f32_e32 v203, v249, v203
	v_cvt_pk_bf16_f32 v203, v10, v203
	v_lshlrev_b32_e32 v10, 16, v204
	v_and_b32_e32 v204, 0xffff0000, v204
	v_add_f32_e32 v10, v70, v10
	v_add_f32_e32 v204, v71, v204
	v_add_f32_e32 v10, v250, v10
	v_add_f32_e32 v204, v251, v204
	v_cvt_pk_bf16_f32 v204, v10, v204
	v_lshlrev_b32_e32 v10, 16, v205
	v_and_b32_e32 v205, 0xffff0000, v205
	v_add_f32_e32 v10, v72, v10
	v_add_f32_e32 v205, v73, v205
	v_add_f32_e32 v10, v252, v10
	v_add_f32_e32 v205, v253, v205
	v_cvt_pk_bf16_f32 v205, v10, v205
	global_store_dwordx4 v[224:225], v[202:205], off offset:256 sc1
	v_lshl_add_u64 v[224:225], v[224:225], 0, s[2:3]
	s_waitcnt vmcnt(14)
; __device__ __forceinline__ unsigned cvt_pk_bf16(float lo, float hi) { unsigned r; asm volatile("v_cvt_pk_bf16_f32 %0, %1, %2" : "=v"(r) : "v"(lo), "v"(hi)); return r; }
; __device__ __forceinline__ float bflo(unsigned w) { return __uint_as_float(w << 16); }
; __device__ __forceinline__ float bfhi(unsigned w) { return __uint_as_float(w & 0xffff0000u); }
; __device__ __forceinline__ void epi_resid(const f32x4 (&acc)[2][2][4][2], const Unit& u, char* Cb, int ldc, const float* bias, int wr, int wc, int fr, int fq) {
;     ...
;             for (int m = 0; m < 4; ++m) { u32x4* q = (u32x4*)(base + (long)(ai * HALF + m * 16) * ldc + bj * HALF);
;                 const u32x4 x = *q; const f32x4 a0 = acc[ai][bj][m][0], a1 = acc[ai][bj][m][1];
;                 u32x4 w;
;                 w.x = cvt_pk_bf16(bflo(x.x) + a0[0] + b0[0], bfhi(x.x) + a0[1] + b0[1]); w.y = cvt_pk_bf16(bflo(x.y) + a0[2] + b0[2], bfhi(x.y) + a0[3] + b0[3]);
;                 w.z = cvt_pk_bf16(bflo(x.z) + a1[0] + b1[0], bfhi(x.z) + a1[1] + b1[1]); w.w = cvt_pk_bf16(bflo(x.w) + a1[2] + b1[2], bfhi(x.w) + a1[3] + b1[3]);
;                 *q = w; } }
	v_lshlrev_b32_e32 v10, 16, v134
	v_and_b32_e32 v134, 0xffff0000, v134
	v_add_f32_e32 v10, v58, v10
	v_add_f32_e32 v134, v59, v134
	v_add_f32_e32 v10, v246, v10
	v_add_f32_e32 v134, v247, v134
	v_cvt_pk_bf16_f32 v134, v10, v134
	v_lshlrev_b32_e32 v10, 16, v135
	v_and_b32_e32 v135, 0xffff0000, v135
	v_add_f32_e32 v10, v60, v10
	v_add_f32_e32 v135, v61, v135
	v_add_f32_e32 v10, v248, v10
	v_add_f32_e32 v135, v249, v135
	v_cvt_pk_bf16_f32 v135, v10, v135
	v_lshlrev_b32_e32 v10, 16, v136
	v_and_b32_e32 v136, 0xffff0000, v136
	v_add_f32_e32 v10, v54, v10
	v_add_f32_e32 v136, v55, v136
	v_add_f32_e32 v10, v250, v10
	v_add_f32_e32 v136, v251, v136
	v_cvt_pk_bf16_f32 v136, v10, v136
	v_lshlrev_b32_e32 v10, 16, v137
	v_and_b32_e32 v137, 0xffff0000, v137
	v_add_f32_e32 v10, v56, v10
	v_add_f32_e32 v137, v57, v137
	v_add_f32_e32 v10, v252, v10
	v_add_f32_e32 v137, v253, v137
	v_cvt_pk_bf16_f32 v137, v10, v137
	global_store_dwordx4 v[224:225], v[134:137], off offset:256 sc1
	v_lshl_add_u64 v[224:225], v[224:225], 0, s[14:15]
	s_waitcnt vmcnt(13)
	v_lshlrev_b32_e32 v10, 16, v138
	v_and_b32_e32 v138, 0xffff0000, v138
	v_add_f32_e32 v10, v42, v10
	v_add_f32_e32 v138, v43, v138
	v_add_f32_e32 v10, v246, v10
	v_add_f32_e32 v138, v247, v138
	v_cvt_pk_bf16_f32 v138, v10, v138
	v_lshlrev_b32_e32 v10, 16, v139
	v_and_b32_e32 v139, 0xffff0000, v139
	v_add_f32_e32 v10, v44, v10
	v_add_f32_e32 v139, v45, v139
	v_add_f32_e32 v10, v248, v10
	v_add_f32_e32 v139, v249, v139
	v_cvt_pk_bf16_f32 v139, v10, v139
	v_lshlrev_b32_e32 v10, 16, v140
	v_and_b32_e32 v140, 0xffff0000, v140
	v_add_f32_e32 v10, v38, v10
	v_add_f32_e32 v140, v39, v140
	v_add_f32_e32 v10, v250, v10
	v_add_f32_e32 v140, v251, v140
	v_cvt_pk_bf16_f32 v140, v10, v140
	v_lshlrev_b32_e32 v10, 16, v141
	v_and_b32_e32 v141, 0xffff0000, v141
	v_add_f32_e32 v10, v40, v10
	v_add_f32_e32 v141, v41, v141
	v_add_f32_e32 v10, v252, v10
	v_add_f32_e32 v141, v253, v141
	v_cvt_pk_bf16_f32 v141, v10, v141
	global_store_dwordx4 v[224:225], v[138:141], off offset:256 sc1
	v_lshl_add_u64 v[224:225], v[224:225], 0, s[14:15]
	s_waitcnt vmcnt(12)
	v_lshlrev_b32_e32 v10, 16, v142
	v_and_b32_e32 v142, 0xffff0000, v142
	v_add_f32_e32 v10, v26, v10
	v_add_f32_e32 v142, v27, v142
	v_add_f32_e32 v10, v246, v10
	v_add_f32_e32 v142, v247, v142
	v_cvt_pk_bf16_f32 v142, v10, v142
	v_lshlrev_b32_e32 v10, 16, v143
	v_and_b32_e32 v143, 0xffff0000, v143
	v_add_f32_e32 v10, v28, v10
	v_add_f32_e32 v143, v29, v143
	v_add_f32_e32 v10, v248, v10
	v_add_f32_e32 v143, v249, v143
	v_cvt_pk_bf16_f32 v143, v10, v143
	v_lshlrev_b32_e32 v10, 16, v144
	v_and_b32_e32 v144, 0xffff0000, v144
	v_add_f32_e32 v10, v22, v10
	v_add_f32_e32 v144, v23, v144
	v_add_f32_e32 v10, v250, v10
	v_add_f32_e32 v144, v251, v144
	v_cvt_pk_bf16_f32 v144, v10, v144
	v_lshlrev_b32_e32 v10, 16, v145
	v_and_b32_e32 v145, 0xffff0000, v145
	v_add_f32_e32 v10, v24, v10
	v_add_f32_e32 v145, v25, v145
	v_add_f32_e32 v10, v252, v10
	v_add_f32_e32 v145, v253, v145
	v_cvt_pk_bf16_f32 v145, v10, v145
	global_store_dwordx4 v[224:225], v[142:145], off offset:256 sc1
	v_lshl_add_u64 v[224:225], v[224:225], 0, s[14:15]
	s_waitcnt vmcnt(11)
	v_lshlrev_b32_e32 v10, 16, v146
	v_and_b32_e32 v146, 0xffff0000, v146
	v_add_f32_e32 v10, v4, v10
	v_add_f32_e32 v146, v5, v146
	v_add_f32_e32 v10, v246, v10
	v_add_f32_e32 v146, v247, v146
	v_cvt_pk_bf16_f32 v146, v10, v146
	v_lshlrev_b32_e32 v10, 16, v147
	v_and_b32_e32 v147, 0xffff0000, v147
	v_add_f32_e32 v10, v6, v10
	v_add_f32_e32 v147, v7, v147
	v_add_f32_e32 v10, v248, v10
	v_add_f32_e32 v147, v249, v147
	v_cvt_pk_bf16_f32 v147, v10, v147
	v_lshlrev_b32_e32 v10, 16, v148
	v_and_b32_e32 v148, 0xffff0000, v148
	v_add_f32_e32 v10, v0, v10
	v_add_f32_e32 v148, v1, v148
	v_add_f32_e32 v10, v250, v10
	v_add_f32_e32 v148, v251, v148
	v_cvt_pk_bf16_f32 v148, v10, v148
	v_lshlrev_b32_e32 v10, 16, v149
	v_and_b32_e32 v149, 0xffff0000, v149
	v_add_f32_e32 v10, v2, v10
	v_add_f32_e32 v149, v3, v149
	v_add_f32_e32 v10, v252, v10
	v_add_f32_e32 v149, v253, v149
	v_cvt_pk_bf16_f32 v149, v10, v149
	global_store_dwordx4 v[224:225], v[146:149], off offset:256 sc1
	s_mov_b64 s[72:73], 0
